# GEMM_in epilogue: rope-table loads of all four token groups issued at the first rope site (one round trip instead of four)
# baseline (speedup 1.0000x reference)
; DI void gemm_tile(const Params& p, const GemmJob& j, int mt, int nt, char* smem) {
;     ...
; #pragma unroll
;       for (int ni = 0; ni < 4; ++ni) {
;         const int tl = 128 * wt + 32 * ni + r, t = t0 + tl; const float rs = rstd_s[tl];
; #pragma unroll
;         for (int mi = 0; mi < 2; ++mi) {
;           float v[16];
; #pragma unroll
;           for (int i = 0; i < 16; ++i) v[i] = acc[mi][ni][i] * rs;
;           if (s.kind == K_ROPE && mi == 0) {
; #pragma unroll
;             for (int i = 0; i < 4; ++i) {
;               const f32x2 cs = p.rope[(size_t)t * 8 + 4 * h + i]; const float x1 = v[i], x2 = v[i + 4];
;               v[i] = x1 * cs[0] - x2 * cs[1]; v[i + 4] = x2 * cs[0] + x1 * cs[1];
;             }
;           }
.LBB0_121:
	s_lshl_b64 s[6:7], s[6:7], 5
	s_add_u32 s6, s64, s6
	s_addc_u32 s7, s65, s7
	s_and_b32 s8, s72, 0xffffff80
	v_or_b32_e32 v147, s8, v144
	v_lshl_add_u32 v0, v147, 2, 0
	v_add_u32_e32 v0, 0x12000, v0
	ds_read_b32 v130, v0
	s_load_dwordx2 s[70:71], s[6:7], 0x160
	s_load_dword s58, s[6:7], 0x174
	v_add_u32_e32 v142, s10, v147
	v_lshlrev_b32_e32 v148, 2, v146
	s_waitcnt lgkmcnt(0)
	v_mul_f32_e32 v134, v116, v130
	v_mov_b32_e32 v116, v121
	s_cmp_eq_u32 s71, 2
	v_pk_mul_f32 v[136:137], v[116:117], v[130:131] op_sel_hi:[1,0]
	v_mov_b32_e32 v121, v122
	v_mov_b32_e32 v116, v123
	v_mov_b32_e32 v117, v124
	s_cselect_b64 s[8:9], -1, 0
	v_ashrrev_i32_e32 v143, 31, v142
	v_pk_mul_f32 v[138:139], v[114:115], v[130:131] op_sel_hi:[1,0]
	v_pk_mul_f32 v[132:133], v[118:119], v[130:131] op_sel_hi:[1,0]
	v_pk_mul_f32 v[114:115], v[120:121], v[130:131] op_sel_hi:[1,0]
	v_pk_mul_f32 v[120:121], v[116:117], v[130:131] op_sel_hi:[1,0]
	v_mov_b32_e32 v116, v125
	v_mov_b32_e32 v117, v126
	v_mov_b32_e32 v118, v127
	v_mov_b32_e32 v119, v128
	v_lshlrev_b64 v[140:141], 6, v[142:143]
	v_pk_mul_f32 v[116:117], v[116:117], v[130:131] op_sel_hi:[1,0]
	v_pk_mul_f32 v[122:123], v[118:119], v[130:131] op_sel_hi:[1,0]
	v_mul_f32_e32 v119, v129, v130
	s_and_b64 vcc, exec, s[8:9]
	v_lshlrev_b32_e32 v0, 3, v148
	s_cbranch_vccz .LBB0_123
	v_readlane_b32 s12, v229, 29
	v_readlane_b32 s20, v229, 37
	v_readlane_b32 s21, v229, 38
	v_mov_b32_e32 v154, v114
	v_mov_b32_e32 v155, v136
	v_lshl_add_u64 v[124:125], s[20:21], 0, v[140:141]
	v_lshl_add_u64 v[128:129], v[124:125], 0, v[0:1]
	global_load_dwordx4 v[124:127], v[128:129], off offset:16
	global_load_dwordx4 v[150:153], v[128:129], off
	global_load_dwordx4 v[232:235], v[128:129], off offset:2064
	global_load_dwordx4 v[236:239], v[128:129], off offset:2048
	s_mov_b64 s[100:101], 0x1000
	v_lshl_add_u64 v[128:129], v[128:129], 0, s[100:101]
	global_load_dwordx4 v[240:243], v[128:129], off offset:16
	global_load_dwordx4 v[244:247], v[128:129], off
	global_load_dwordx4 v[248:251], v[128:129], off offset:2064
	global_load_dwordx4 v[252:255], v[128:129], off offset:2048
	v_mov_b32_e32 v135, v137
	v_readlane_b32 s13, v229, 30
	v_readlane_b32 s14, v229, 31
	v_readlane_b32 s15, v229, 32
	v_readlane_b32 s16, v229, 33
	v_readlane_b32 s17, v229, 34
	v_readlane_b32 s18, v229, 35
	v_readlane_b32 s19, v229, 36
	v_readlane_b32 s22, v229, 39
	v_readlane_b32 s23, v229, 40
	v_readlane_b32 s24, v229, 41
	v_readlane_b32 s25, v229, 42
	v_readlane_b32 s26, v229, 43
	v_readlane_b32 s27, v229, 44
	s_waitcnt vmcnt(6)
	v_mov_b32_e32 v129, v152
	v_mov_b32_e32 v152, v151
	v_mov_b32_e32 v128, v150
	v_pk_mul_f32 v[150:151], v[132:133], v[152:153]
	s_nop 0
	v_pk_fma_f32 v[150:151], v[138:139], v[128:129], v[150:151] neg_lo:[0,0,1] neg_hi:[0,0,1]
	v_pk_mul_f32 v[138:139], v[138:139], v[152:153]
	v_mov_b32_e32 v152, v124
	v_pk_fma_f32 v[132:133], v[132:133], v[128:129], v[138:139]
	v_pk_mul_f32 v[128:129], v[114:115], v[124:125]
	v_mul_f32_e32 v138, v134, v125
	v_mov_b32_e32 v124, v125
	v_mov_b32_e32 v125, v127
	v_mov_b32_e32 v153, v126
	v_pk_mul_f32 v[124:125], v[154:155], v[124:125]
	s_nop 0
	v_pk_fma_f32 v[134:135], v[134:135], v[152:153], v[124:125] neg_lo:[0,0,1] neg_hi:[0,0,1]
	v_pk_mul_f32 v[124:125], v[136:137], v[126:127]
	v_mov_b32_e32 v137, v135
	v_mov_b32_e32 v129, v124
	v_mov_b32_e32 v139, v125
	v_pk_add_f32 v[124:125], v[128:129], v[138:139]
	v_mov_b32_e32 v138, v150
	v_mov_b32_e32 v139, v151
	v_mov_b32_e32 v114, v124
	v_mov_b32_e32 v136, v125

; DI void gemm_tile(const Params& p, const GemmJob& j, int mt, int nt, char* smem) {
;     ...
; #pragma unroll
;       for (int ni = 0; ni < 4; ++ni) {
;         const int tl = 128 * wt + 32 * ni + r, t = t0 + tl; const float rs = rstd_s[tl];
; #pragma unroll
;         for (int mi = 0; mi < 2; ++mi) {
;           float v[16];
; #pragma unroll
;           for (int i = 0; i < 16; ++i) v[i] = acc[mi][ni][i] * rs;
;           if (s.kind == K_ROPE && mi == 0) {
; #pragma unroll
;             for (int i = 0; i < 4; ++i) {
;               const f32x2 cs = p.rope[(size_t)t * 8 + 4 * h + i]; const float x1 = v[i], x2 = v[i + 4];
;               v[i] = x1 * cs[0] - x2 * cs[1]; v[i + 4] = x2 * cs[0] + x1 * cs[1];
;             }
;           }
.LBB0_159:
	v_or_b32_e32 v99, 32, v147
	v_lshl_add_u32 v98, v99, 2, 0
	v_add_u32_e32 v98, 0x12000, v98
	ds_read_b32 v98, v98
	v_add_u32_e32 v110, s10, v99
	v_ashrrev_i32_e32 v111, 31, v110
	v_lshlrev_b64 v[108:109], 6, v[110:111]
	s_andn2_b64 vcc, exec, s[8:9]
	s_waitcnt lgkmcnt(0)
	v_mul_f32_e32 v102, v84, v98
	v_mov_b32_e32 v84, v89
	v_pk_mul_f32 v[104:105], v[84:85], v[98:99] op_sel_hi:[1,0]
	v_mov_b32_e32 v89, v90
	v_mov_b32_e32 v84, v91
	v_mov_b32_e32 v85, v92
	v_pk_mul_f32 v[106:107], v[82:83], v[98:99] op_sel_hi:[1,0]
	v_pk_mul_f32 v[100:101], v[86:87], v[98:99] op_sel_hi:[1,0]
	v_pk_mul_f32 v[82:83], v[88:89], v[98:99] op_sel_hi:[1,0]
	v_pk_mul_f32 v[86:87], v[84:85], v[98:99] op_sel_hi:[1,0]
	v_mov_b32_e32 v84, v93
	v_mov_b32_e32 v85, v94
	v_mov_b32_e32 v88, v95
	v_mov_b32_e32 v89, v96
	v_cndmask_b32_e64 v90, 0, 1, s[8:9]
	v_pk_mul_f32 v[84:85], v[84:85], v[98:99] op_sel_hi:[1,0]
	v_pk_mul_f32 v[88:89], v[88:89], v[98:99] op_sel_hi:[1,0]
	v_cmp_ne_u32_e64 s[6:7], 1, v90
	v_mul_f32_e32 v91, v97, v98
	s_cbranch_vccnz .LBB0_161
	v_readlane_b32 s12, v229, 29
	v_readlane_b32 s20, v229, 37
	v_readlane_b32 s21, v229, 38
	v_mov_b32_e32 v116, v82
	v_mov_b32_e32 v117, v104
	v_lshl_add_u64 v[92:93], s[20:21], 0, v[108:109]
	v_lshl_add_u64 v[96:97], v[92:93], 0, v[0:1]
	v_mov_b32_e32 v103, v105
	v_readlane_b32 s13, v229, 30
	v_readlane_b32 s14, v229, 31
	v_readlane_b32 s15, v229, 32
	v_readlane_b32 s16, v229, 33
	v_readlane_b32 s17, v229, 34
	v_readlane_b32 s18, v229, 35
	v_readlane_b32 s19, v229, 36
	v_readlane_b32 s22, v229, 39
	v_readlane_b32 s23, v229, 40
	v_readlane_b32 s24, v229, 41
	v_readlane_b32 s25, v229, 42
	v_readlane_b32 s26, v229, 43
	v_readlane_b32 s27, v229, 44
	s_waitcnt vmcnt(4)
	v_mov_b32_e32 v92, v232
	v_mov_b32_e32 v93, v233
	v_mov_b32_e32 v94, v234
	v_mov_b32_e32 v95, v235
	v_mov_b32_e32 v112, v236
	v_mov_b32_e32 v113, v237
	v_mov_b32_e32 v114, v238
	v_mov_b32_e32 v115, v239
	v_mov_b32_e32 v97, v114
	v_mov_b32_e32 v114, v113
	v_mov_b32_e32 v96, v112
	v_pk_mul_f32 v[112:113], v[100:101], v[114:115]
	s_nop 0
	v_pk_fma_f32 v[112:113], v[106:107], v[96:97], v[112:113] neg_lo:[0,0,1] neg_hi:[0,0,1]
	v_pk_mul_f32 v[106:107], v[106:107], v[114:115]
	v_mov_b32_e32 v114, v92
	v_pk_fma_f32 v[100:101], v[100:101], v[96:97], v[106:107]
	v_pk_mul_f32 v[96:97], v[82:83], v[92:93]
	v_mul_f32_e32 v106, v102, v93
	v_mov_b32_e32 v92, v93
	v_mov_b32_e32 v93, v95
	v_mov_b32_e32 v115, v94
	v_pk_mul_f32 v[92:93], v[116:117], v[92:93]
	s_nop 0
	v_pk_fma_f32 v[102:103], v[102:103], v[114:115], v[92:93] neg_lo:[0,0,1] neg_hi:[0,0,1]
	v_pk_mul_f32 v[92:93], v[104:105], v[94:95]
	v_mov_b32_e32 v105, v103
	v_mov_b32_e32 v97, v92
	v_mov_b32_e32 v107, v93
	v_pk_add_f32 v[92:93], v[96:97], v[106:107]
	v_mov_b32_e32 v106, v112
	v_mov_b32_e32 v107, v113
	v_mov_b32_e32 v82, v92
	v_mov_b32_e32 v104, v93

; DI void gemm_tile(const Params& p, const GemmJob& j, int mt, int nt, char* smem) {
;     ...
; #pragma unroll
;       for (int ni = 0; ni < 4; ++ni) {
;         const int tl = 128 * wt + 32 * ni + r, t = t0 + tl; const float rs = rstd_s[tl];
; #pragma unroll
;         for (int mi = 0; mi < 2; ++mi) {
;           float v[16];
; #pragma unroll
;           for (int i = 0; i < 16; ++i) v[i] = acc[mi][ni][i] * rs;
;           if (s.kind == K_ROPE && mi == 0) {
; #pragma unroll
;             for (int i = 0; i < 4; ++i) {
;               const f32x2 cs = p.rope[(size_t)t * 8 + 4 * h + i]; const float x1 = v[i], x2 = v[i + 4];
;               v[i] = x1 * cs[0] - x2 * cs[1]; v[i + 4] = x2 * cs[0] + x1 * cs[1];
;             }
;           }
.LBB0_197:
	v_or_b32_e32 v67, 64, v147
	v_lshl_add_u32 v66, v67, 2, 0
	v_add_u32_e32 v66, 0x12000, v66
	ds_read_b32 v66, v66
	v_add_u32_e32 v78, s10, v67
	v_ashrrev_i32_e32 v79, 31, v78
	v_lshlrev_b64 v[76:77], 6, v[78:79]
	s_and_b64 vcc, exec, s[6:7]
	s_waitcnt lgkmcnt(0)
	v_mul_f32_e32 v70, v52, v66
	v_mov_b32_e32 v52, v57
	v_pk_mul_f32 v[72:73], v[52:53], v[66:67] op_sel_hi:[1,0]
	v_mov_b32_e32 v57, v58
	v_mov_b32_e32 v52, v59
	v_mov_b32_e32 v53, v60
	v_pk_mul_f32 v[74:75], v[50:51], v[66:67] op_sel_hi:[1,0]
	v_pk_mul_f32 v[68:69], v[54:55], v[66:67] op_sel_hi:[1,0]
	v_pk_mul_f32 v[50:51], v[56:57], v[66:67] op_sel_hi:[1,0]
	v_pk_mul_f32 v[54:55], v[52:53], v[66:67] op_sel_hi:[1,0]
	v_mov_b32_e32 v52, v61
	v_mov_b32_e32 v53, v62
	v_mov_b32_e32 v56, v63
	v_mov_b32_e32 v57, v64
	v_pk_mul_f32 v[52:53], v[52:53], v[66:67] op_sel_hi:[1,0]
	v_pk_mul_f32 v[56:57], v[56:57], v[66:67] op_sel_hi:[1,0]
	v_mul_f32_e32 v59, v65, v66
	s_cbranch_vccnz .LBB0_199
	v_readlane_b32 s12, v229, 29
	v_readlane_b32 s20, v229, 37
	v_readlane_b32 s21, v229, 38
	v_mov_b32_e32 v84, v50
	v_mov_b32_e32 v85, v72
	v_lshl_add_u64 v[60:61], s[20:21], 0, v[76:77]
	v_lshl_add_u64 v[64:65], v[60:61], 0, v[0:1]
	v_mov_b32_e32 v71, v73
	v_readlane_b32 s13, v229, 30
	v_readlane_b32 s14, v229, 31
	v_readlane_b32 s15, v229, 32
	v_readlane_b32 s16, v229, 33
	v_readlane_b32 s17, v229, 34
	v_readlane_b32 s18, v229, 35
	v_readlane_b32 s19, v229, 36
	v_readlane_b32 s22, v229, 39
	v_readlane_b32 s23, v229, 40
	v_readlane_b32 s24, v229, 41
	v_readlane_b32 s25, v229, 42
	v_readlane_b32 s26, v229, 43
	v_readlane_b32 s27, v229, 44
	s_waitcnt vmcnt(2)
	v_mov_b32_e32 v60, v240
	v_mov_b32_e32 v61, v241
	v_mov_b32_e32 v62, v242
	v_mov_b32_e32 v63, v243
	v_mov_b32_e32 v80, v244
	v_mov_b32_e32 v81, v245
	v_mov_b32_e32 v82, v246
	v_mov_b32_e32 v83, v247
	v_mov_b32_e32 v65, v82
	v_mov_b32_e32 v82, v81
	v_mov_b32_e32 v64, v80
	v_pk_mul_f32 v[80:81], v[68:69], v[82:83]
	s_nop 0
	v_pk_fma_f32 v[80:81], v[74:75], v[64:65], v[80:81] neg_lo:[0,0,1] neg_hi:[0,0,1]
	v_pk_mul_f32 v[74:75], v[74:75], v[82:83]
	v_mov_b32_e32 v82, v60
	v_pk_fma_f32 v[68:69], v[68:69], v[64:65], v[74:75]
	v_pk_mul_f32 v[64:65], v[50:51], v[60:61]
	v_mul_f32_e32 v74, v70, v61
	v_mov_b32_e32 v60, v61
	v_mov_b32_e32 v61, v63
	v_mov_b32_e32 v83, v62
	v_pk_mul_f32 v[60:61], v[84:85], v[60:61]
	s_nop 0
	v_pk_fma_f32 v[70:71], v[70:71], v[82:83], v[60:61] neg_lo:[0,0,1] neg_hi:[0,0,1]
	v_pk_mul_f32 v[60:61], v[72:73], v[62:63]
	v_mov_b32_e32 v73, v71
	v_mov_b32_e32 v65, v60
	v_mov_b32_e32 v75, v61
	v_pk_add_f32 v[60:61], v[64:65], v[74:75]
	v_mov_b32_e32 v74, v80
	v_mov_b32_e32 v75, v81
	v_mov_b32_e32 v50, v60
	v_mov_b32_e32 v72, v61

; DI void gemm_tile(const Params& p, const GemmJob& j, int mt, int nt, char* smem) {
;     ...
; #pragma unroll
;       for (int ni = 0; ni < 4; ++ni) {
;         const int tl = 128 * wt + 32 * ni + r, t = t0 + tl; const float rs = rstd_s[tl];
; #pragma unroll
;         for (int mi = 0; mi < 2; ++mi) {
;           float v[16];
; #pragma unroll
;           for (int i = 0; i < 16; ++i) v[i] = acc[mi][ni][i] * rs;
;           if (s.kind == K_ROPE && mi == 0) {
; #pragma unroll
;             for (int i = 0; i < 4; ++i) {
;               const f32x2 cs = p.rope[(size_t)t * 8 + 4 * h + i]; const float x1 = v[i], x2 = v[i + 4];
;               v[i] = x1 * cs[0] - x2 * cs[1]; v[i + 4] = x2 * cs[0] + x1 * cs[1];
;             }
;           }
.LBB0_235:
	v_or_b32_e32 v35, 0x60, v147
	v_lshl_add_u32 v34, v35, 2, 0
	v_add_u32_e32 v34, 0x12000, v34
	ds_read_b32 v34, v34
	v_add_u32_e32 v46, s10, v35
	v_ashrrev_i32_e32 v47, 31, v46
	v_lshlrev_b64 v[44:45], 6, v[46:47]
	s_and_b64 vcc, exec, s[6:7]
	s_waitcnt lgkmcnt(0)
	v_mul_f32_e32 v38, v20, v34
	v_mov_b32_e32 v20, v25
	v_pk_mul_f32 v[40:41], v[20:21], v[34:35] op_sel_hi:[1,0]
	v_mov_b32_e32 v25, v26
	v_mov_b32_e32 v20, v27
	v_mov_b32_e32 v21, v28
	v_pk_mul_f32 v[42:43], v[18:19], v[34:35] op_sel_hi:[1,0]
	v_pk_mul_f32 v[36:37], v[22:23], v[34:35] op_sel_hi:[1,0]
	v_pk_mul_f32 v[18:19], v[24:25], v[34:35] op_sel_hi:[1,0]
	v_pk_mul_f32 v[22:23], v[20:21], v[34:35] op_sel_hi:[1,0]
	v_mov_b32_e32 v20, v29
	v_mov_b32_e32 v21, v30
	v_mov_b32_e32 v24, v31
	v_mov_b32_e32 v25, v32
	v_pk_mul_f32 v[20:21], v[20:21], v[34:35] op_sel_hi:[1,0]
	v_pk_mul_f32 v[24:25], v[24:25], v[34:35] op_sel_hi:[1,0]
	v_mul_f32_e32 v27, v33, v34
	s_cbranch_vccnz .LBB0_237
	v_readlane_b32 s12, v229, 29
	v_readlane_b32 s20, v229, 37
	v_readlane_b32 s21, v229, 38
	v_mov_b32_e32 v52, v18
	v_mov_b32_e32 v53, v40
	v_lshl_add_u64 v[28:29], s[20:21], 0, v[44:45]
	v_lshl_add_u64 v[32:33], v[28:29], 0, v[0:1]
	v_mov_b32_e32 v39, v41
	v_readlane_b32 s13, v229, 30
	v_readlane_b32 s14, v229, 31
	v_readlane_b32 s15, v229, 32
	v_readlane_b32 s16, v229, 33
	v_readlane_b32 s17, v229, 34
	v_readlane_b32 s18, v229, 35
	v_readlane_b32 s19, v229, 36
	v_readlane_b32 s22, v229, 39
	v_readlane_b32 s23, v229, 40
	v_readlane_b32 s24, v229, 41
	v_readlane_b32 s25, v229, 42
	v_readlane_b32 s26, v229, 43
	v_readlane_b32 s27, v229, 44
	s_waitcnt vmcnt(0)
	v_mov_b32_e32 v28, v248
	v_mov_b32_e32 v29, v249
	v_mov_b32_e32 v30, v250
	v_mov_b32_e32 v31, v251
	v_mov_b32_e32 v48, v252
	v_mov_b32_e32 v49, v253
	v_mov_b32_e32 v50, v254
	v_mov_b32_e32 v51, v255
	v_mov_b32_e32 v33, v50
	v_mov_b32_e32 v50, v49
	v_mov_b32_e32 v32, v48
	v_pk_mul_f32 v[48:49], v[36:37], v[50:51]
	s_nop 0
	v_pk_fma_f32 v[48:49], v[42:43], v[32:33], v[48:49] neg_lo:[0,0,1] neg_hi:[0,0,1]
	v_pk_mul_f32 v[42:43], v[42:43], v[50:51]
	v_mov_b32_e32 v50, v28
	v_pk_fma_f32 v[36:37], v[36:37], v[32:33], v[42:43]
	v_pk_mul_f32 v[32:33], v[18:19], v[28:29]
	v_mul_f32_e32 v42, v38, v29
	v_mov_b32_e32 v28, v29
	v_mov_b32_e32 v29, v31
	v_mov_b32_e32 v51, v30
	v_pk_mul_f32 v[28:29], v[52:53], v[28:29]
	s_nop 0
	v_pk_fma_f32 v[38:39], v[38:39], v[50:51], v[28:29] neg_lo:[0,0,1] neg_hi:[0,0,1]
	v_pk_mul_f32 v[28:29], v[40:41], v[30:31]
	v_mov_b32_e32 v41, v39
	v_mov_b32_e32 v33, v28
	v_mov_b32_e32 v43, v29
	v_pk_add_f32 v[28:29], v[32:33], v[42:43]
	v_mov_b32_e32 v42, v48
	v_mov_b32_e32 v43, v49
	v_mov_b32_e32 v18, v28
	v_mov_b32_e32 v40, v29
